# rwprep loop processes two items per iteration (second register set, both items' loads in flight before one wait)
# baseline (speedup 1.0000x reference)
; __device__ __forceinline__ int tid_of(int wv) { int t = wv * 64 + lane_id(); asm volatile("" : "+v"(t)); return t; }
; __device__ __forceinline__ int bidx() { int t = blockIdx.x; asm volatile("" : "+s"(t)); return t; }
; __device__ __forceinline__ void phase_rwprep(const PP& p, int l) {
;     ...
;     for (int idx = bidx() * 512 + tid_of(p.wv); idx < MROWS * 112; idx += nth) {
;         const int row = idx / 112, qd = idx - row * 112, col0 = 8 * qd, zc = col0 < 768 ? col0 : col0 + 384;
;         const int b = row / TT, j = row - b * TT;
;         const bool hp = (j != 0) && (j != CTX), hn = (j != CTX - 1) && (j != TT - 1);
;         const bf16_t* q = Z + (size_t)row * ZLD + zc;
;         const u32x4 cu = *(const u32x4*)q;
;         const u32x4 pv = hp ? *(const u32x4*)(q - ZLD) : (u32x4){0u, 0u, 0u, 0u};
;         const u32x4 nx = hn ? *(const u32x4*)(q + ZLD) : (u32x4){0u, 0u, 0u, 0u};
.LBB0_383:
	s_mov_b32 s98, 0x20000
	s_mov_b32 s99, 0x19ffff
	v_readlane_b32 s0, v254, 17
	v_readlane_b32 s6, v252, 0
	s_nop 0
	v_mov_b32_e32 v1, s0
	ds_read_b64 v[2:3], v1
	v_readlane_b32 s0, v254, 58
	v_readlane_b32 s1, v254, 59
	s_mulk_i32 s0, 0x580
	s_mov_b32 s1, s13
	v_writelane_b32 v254, s0, 62
	v_mov_b32_e32 v1, v162
	s_waitcnt lgkmcnt(0)
	v_readfirstlane_b32 s5, v3
	v_writelane_b32 v254, s1, 63
	v_lshl_add_u32 v14, s6, 9, v1
	s_mov_b32 s0, 0x39c000
	v_readfirstlane_b32 s4, v2
	v_cmp_gt_i32_e32 vcc, s0, v14
	s_and_saveexec_b64 s[0:1], vcc
	s_cbranch_execz .LBB0_392
	v_readlane_b32 s22, v254, 62
	v_readlane_b32 s23, v254, 63
	s_lshl_b64 s[22:23], s[22:23], 2
	s_add_u32 s4, s4, s22
	v_lshlrev_b32_e32 v1, 3, v1
	s_addc_u32 s5, s5, s23
	v_lshl_add_u32 v16, s6, 12, v1
	s_mov_b64 s[22:23], 0
	s_branch .LBB0_386
.LBB0_386:
	s_mov_b32 s6, 0x92492493
	v_mul_hi_i32 v1, v14, s6
	v_add_u32_e32 v1, v1, v14
	v_lshrrev_b32_e32 v2, 31, v1
	v_ashrrev_i32_e32 v1, 6, v1
	v_add_u32_e32 v1, v1, v2
	s_movk_i32 s6, 0xff90
	v_mad_u64_u32 v[20:21], s[6:7], v1, s6, v[14:15]
	s_movk_i32 s6, 0xfc80
	s_nop 0
	v_mad_u64_u32 v[18:19], s[6:7], v1, s6, v[16:17]
	s_movk_i32 s6, 0x60
	s_nop 0
	v_cmp_gt_i32_e32 vcc, s6, v20
	v_readlane_b32 s6, v253, 28
	v_add_u32_e32 v2, 0x180, v18
	v_readlane_b32 s7, v253, 29
	v_cndmask_b32_e32 v22, v2, v18, vcc
	v_ashrrev_i32_e32 v23, 31, v22
	v_mov_b64_e32 v[2:3], s[6:7]
	v_mad_i64_i32 v[2:3], s[6:7], v1, s31, v[2:3]
	v_lshl_add_u64 v[24:25], v[22:23], 1, v[2:3]
	global_load_dwordx4 v[2:5], v[24:25], off
	s_mov_b32 s6, 0x8dda5203
	v_mul_hi_i32 v6, v14, s6
	v_add_u32_e32 v6, v6, v14
	v_lshrrev_b32_e32 v7, 31, v6
	v_ashrrev_i32_e32 v6, 19, v6
	v_add_u32_e32 v6, v6, v7
	v_mad_i32_i24 v7, v6, s51, v1
	v_and_b32_e32 v8, 0xfffffeff, v7
	v_mov_b32_e32 v6, 0
	v_cmp_ne_u32_e32 vcc, 0, v8
	v_mov_b32_e32 v10, 0
	v_mov_b32_e32 v11, 0
	v_mov_b32_e32 v12, 0
	v_mov_b32_e32 v13, 0
	s_and_saveexec_b64 s[24:25], vcc
	s_cbranch_execz .Lrwp_388_A
	v_add_co_u32_e32 v8, vcc, 0xfffff000, v24
	s_nop 1
	v_addc_co_u32_e32 v9, vcc, -1, v25, vcc
	global_load_dwordx4 v[10:13], v[8:9], off offset:-1840

; __device__ __forceinline__ float bflo(unsigned u) { return __uint_as_float(u << 16); }
; __device__ __forceinline__ float bfhi(unsigned u) { return __uint_as_float(u & 0xFFFF0000u); }
; __device__ __forceinline__ float tanhf_(float x) { return 1.f - 2.f * rcpf_(1.f + __expf(2.f * x)); }
; __device__ __forceinline__ void phase_rwprep(const PP& p, int l) {
;     ...
;         const int row = idx / 112, qd = idx - row * 112, col0 = 8 * qd, zc = col0 < 768 ? col0 : col0 + 384;
;         const int b = row / TT, j = row - b * TT;
;         const bool hp = (j != 0) && (j != CTX), hn = (j != CTX - 1) && (j != TT - 1);
;         const bf16_t* q = Z + (size_t)row * ZLD + zc;
;         const u32x4 cu = *(const u32x4*)q;
;         const u32x4 pv = hp ? *(const u32x4*)(q - ZLD) : (u32x4){0u, 0u, 0u, 0u};
;         const u32x4 nx = hn ? *(const u32x4*)(q + ZLD) : (u32x4){0u, 0u, 0u, 0u};
;         const f32x4 m0 = *(const f32x4*)(mu + zc), m1 = *(const f32x4*)(mu + zc + 4);
;         const f32x4 c0 = (f32x4){bflo(cu.x), bfhi(cu.x), bflo(cu.y), bfhi(cu.y)}, c1 = (f32x4){bflo(cu.z), bfhi(cu.z), bflo(cu.w), bfhi(cu.w)};
;         const f32x4 a0 = (f32x4){bflo(pv.x), bfhi(pv.x), bflo(pv.y), bfhi(pv.y)}, a1 = (f32x4){bflo(pv.z), bfhi(pv.z), bflo(pv.w), bfhi(pv.w)};
;         const f32x4 n0 = (f32x4){bflo(nx.x), bfhi(nx.x), bflo(nx.y), bfhi(nx.y)}, n1 = (f32x4){bflo(nx.z), bfhi(nx.z), bflo(nx.w), bfhi(nx.w)};
;         f32x4 v0 = c0 + ((a0 + n0) * 0.5f - c0) * m0, v1 = c1 + ((a1 + n1) * 0.5f - c1) * m1;
;         if (col0 >= 768 && col0 < 832) {
; #pragma unroll
;             for (int i = 0; i < 4; ++i) { v0[i] = tanhf_(v0[i]); v1[i] = tanhf_(v1[i]); }
.Lrwp_390_A:
	s_or_b64 exec, exec, s[24:25]
	v_lshl_add_u64 v[26:27], v[22:23], 2, s[4:5]
	global_load_dwordx4 v[22:25], v[26:27], off
	s_nop 0
	global_load_dwordx4 v[26:29], v[26:27], off offset:16
	v_add_u32_e32 v56, s98, v14
	v_lshl_add_u32 v58, s98, 3, v16
	s_mov_b64 s[36:37], exec
	v_cmp_ge_i32_e32 vcc, s99, v56
	s_and_b64 s[28:29], vcc, exec
	s_mov_b64 exec, s[28:29]
	s_cbranch_execz .Lrwp_skipB1
	s_mov_b32 s6, 0x92492493
	v_mul_hi_i32 v43, v56, s6
	v_add_u32_e32 v43, v43, v56
	v_lshrrev_b32_e32 v44, 31, v43
	v_ashrrev_i32_e32 v43, 6, v43
	v_add_u32_e32 v43, v43, v44
	s_movk_i32 s6, 0xff90
	v_mad_u64_u32 v[62:63], s[6:7], v43, s6, v[56:57]
	s_movk_i32 s6, 0xfc80
	s_nop 0
	v_mad_u64_u32 v[60:61], s[6:7], v43, s6, v[58:59]
	s_movk_i32 s6, 0x60
	s_nop 0
	v_cmp_gt_i32_e32 vcc, s6, v62
	v_readlane_b32 s6, v253, 28
	v_add_u32_e32 v44, 0x180, v60
	v_readlane_b32 s7, v253, 29
	v_cndmask_b32_e32 v64, v44, v60, vcc
	v_ashrrev_i32_e32 v65, 31, v64
	v_mov_b64_e32 v[44:45], s[6:7]
	v_mad_i64_i32 v[44:45], s[6:7], v43, s31, v[44:45]
	v_lshl_add_u64 v[66:67], v[64:65], 1, v[44:45]
	global_load_dwordx4 v[44:47], v[66:67], off
	s_mov_b32 s6, 0x8dda5203
	v_mul_hi_i32 v48, v56, s6
	v_add_u32_e32 v48, v48, v56
	v_lshrrev_b32_e32 v49, 31, v48
	v_ashrrev_i32_e32 v48, 19, v48
	v_add_u32_e32 v48, v48, v49
	v_mad_i32_i24 v49, v48, s51, v43
	v_and_b32_e32 v50, 0xfffffeff, v49
	v_mov_b32_e32 v48, 0
	v_cmp_ne_u32_e32 vcc, 0, v50
	v_mov_b32_e32 v52, 0
	v_mov_b32_e32 v53, 0
	v_mov_b32_e32 v54, 0
	v_mov_b32_e32 v55, 0
	s_and_saveexec_b64 s[24:25], vcc
	s_cbranch_execz .Lrwp_388_B
	v_add_co_u32_e32 v50, vcc, 0xfffff000, v66
	s_nop 1
	v_addc_co_u32_e32 v51, vcc, -1, v67, vcc
	global_load_dwordx4 v[52:55], v[50:51], off offset:-1840
.Lrwp_388_B:
	s_or_b64 exec, exec, s[24:25]
	v_and_b32_e32 v49, 0xffffdfff, v49
	s_movk_i32 s6, 0xff
	v_cmp_ne_u32_e32 vcc, s6, v49
	v_mov_b32_e32 v49, 0
	v_mov_b32_e32 v50, 0
	v_mov_b32_e32 v51, 0
	s_and_saveexec_b64 s[24:25], vcc
	s_cbranch_execz .Lrwp_390_B
	v_add_co_u32_e32 v48, vcc, 0x1000, v66
	s_nop 1
	v_addc_co_u32_e32 v49, vcc, 0, v67, vcc
	global_load_dwordx4 v[48:51], v[48:49], off offset:1840
.Lrwp_390_B:
	s_or_b64 exec, exec, s[24:25]
	v_lshl_add_u64 v[68:69], v[64:65], 2, s[4:5]
	global_load_dwordx4 v[64:67], v[68:69], off
	s_nop 0
	global_load_dwordx4 v[68:71], v[68:69], off offset:16
.Lrwp_skipB1:
	s_mov_b64 exec, s[36:37]
	s_waitcnt vmcnt(0)
	v_lshlrev_b32_e32 v30, 16, v2
	v_and_b32_e32 v31, 0xffff0000, v2
	v_lshlrev_b32_e32 v2, 16, v3
	v_and_b32_e32 v3, 0xffff0000, v3
	v_lshlrev_b32_e32 v32, 16, v4
	v_and_b32_e32 v33, 0xffff0000, v4
	v_lshlrev_b32_e32 v34, 16, v5
	v_and_b32_e32 v35, 0xffff0000, v5
	v_lshlrev_b32_e32 v4, 16, v10
	v_and_b32_e32 v5, 0xffff0000, v10
	v_lshlrev_b32_e32 v10, 16, v11
	v_and_b32_e32 v11, 0xffff0000, v11
	v_lshlrev_b32_e32 v36, 16, v12
	v_and_b32_e32 v37, 0xffff0000, v12
	v_lshlrev_b32_e32 v12, 16, v13
	v_and_b32_e32 v13, 0xffff0000, v13
	v_lshlrev_b32_e32 v38, 16, v6
	v_and_b32_e32 v39, 0xffff0000, v6
	v_lshlrev_b32_e32 v6, 16, v7
	v_and_b32_e32 v7, 0xffff0000, v7
	v_lshlrev_b32_e32 v40, 16, v8
	v_and_b32_e32 v41, 0xffff0000, v8
	v_lshlrev_b32_e32 v8, 16, v9
	v_and_b32_e32 v9, 0xffff0000, v9
	v_and_b32_e32 v15, -8, v20
	v_pk_add_f32 v[6:7], v[10:11], v[6:7]
	v_pk_add_f32 v[4:5], v[4:5], v[38:39]
	v_xor_b32_e32 v11, 0x80000000, v31
	v_xor_b32_e32 v10, 0x80000000, v30
	v_xor_b32_e32 v21, 0x80000000, v3
	v_xor_b32_e32 v20, 0x80000000, v2
	v_pk_add_f32 v[8:9], v[12:13], v[8:9]
	v_pk_add_f32 v[12:13], v[36:37], v[40:41]
	v_xor_b32_e32 v37, 0x80000000, v33
	v_xor_b32_e32 v36, 0x80000000, v32
	v_xor_b32_e32 v39, 0x80000000, v35
	v_xor_b32_e32 v38, 0x80000000, v34
	v_pk_fma_f32 v[10:11], v[4:5], 0.5, v[10:11] op_sel_hi:[1,0,1]
	v_pk_fma_f32 v[4:5], v[6:7], 0.5, v[20:21] op_sel_hi:[1,0,1]
	v_pk_fma_f32 v[6:7], v[12:13], 0.5, v[36:37] op_sel_hi:[1,0,1]
	v_pk_fma_f32 v[12:13], v[8:9], 0.5, v[38:39] op_sel_hi:[1,0,1]
	s_movk_i32 s6, 0x60
	v_cmp_eq_u32_e32 vcc, s6, v15
	v_pk_fma_f32 v[4:5], v[24:25], v[4:5], v[2:3]
	v_pk_fma_f32 v[8:9], v[22:23], v[10:11], v[30:31]
	v_pk_fma_f32 v[2:3], v[28:29], v[12:13], v[34:35]
	v_pk_fma_f32 v[6:7], v[26:27], v[6:7], v[32:33]
	s_and_saveexec_b64 s[24:25], vcc
	s_cbranch_execz .Lrwp_noth_A
	v_add_f32_e32 v2, v2, v2
	v_add_f32_e32 v5, v5, v5
	v_mul_f32_e32 v2, 0x3fb8aa3b, v2
	v_mul_f32_e32 v5, 0x3fb8aa3b, v5
	v_exp_f32_e32 v2, v2
	v_exp_f32_e32 v5, v5
	v_add_f32_e32 v6, v6, v6
	v_add_f32_e32 v9, v9, v9
	v_add_f32_e32 v7, v7, v7
	v_mul_f32_e32 v6, 0x3fb8aa3b, v6
	v_mul_f32_e32 v9, 0x3fb8aa3b, v9
	v_mul_f32_e32 v7, 0x3fb8aa3b, v7
	v_exp_f32_e32 v6, v6
	v_exp_f32_e32 v9, v9
	v_exp_f32_e32 v7, v7
	v_add_f32_e32 v11, 1.0, v2
	v_add_f32_e32 v2, 1.0, v5
	v_add_f32_e32 v8, v8, v8
	v_add_f32_e32 v4, v4, v4
	v_rcp_f32_e64 v5, -v2
	v_add_f32_e32 v2, v3, v3
	v_mul_f32_e32 v8, 0x3fb8aa3b, v8
	v_mul_f32_e32 v4, 0x3fb8aa3b, v4
	v_mul_f32_e32 v2, 0x3fb8aa3b, v2
	v_exp_f32_e32 v8, v8
	v_add_f32_e32 v10, 1.0, v6
	v_add_f32_e32 v6, 1.0, v9
	v_exp_f32_e32 v4, v4
	v_add_f32_e32 v9, 1.0, v7
	v_exp_f32_e32 v7, v2
	v_add_f32_e32 v8, 1.0, v8
	v_add_f32_e32 v4, 1.0, v4
	v_rcp_f32_e64 v3, -v6
	v_add_f32_e32 v6, 1.0, v7
	v_rcp_f32_e64 v4, -v4
	v_rcp_f32_e64 v2, -v8
	v_rcp_f32_e64 v7, -v6
	v_rcp_f32_e64 v6, -v11
	v_rcp_f32_e64 v11, -v9
	v_rcp_f32_e64 v10, -v10
	v_pk_fma_f32 v[4:5], v[4:5], 2.0, 1.0 op_sel_hi:[1,0,0]
	v_pk_fma_f32 v[8:9], v[2:3], 2.0, 1.0 op_sel_hi:[1,0,0]
	v_pk_fma_f32 v[2:3], v[6:7], 2.0, 1.0 op_sel_hi:[1,0,0]
	v_pk_fma_f32 v[6:7], v[10:11], 2.0, 1.0 op_sel_hi:[1,0,0]
; __device__ __forceinline__ unsigned pk2(float lo, float hi) { f32x2 f; f.x = lo; f.y = hi; return __builtin_bit_cast(unsigned, __builtin_convertvector(f, bf16v2_t)); }
; __device__ __forceinline__ float bflo(unsigned u) { return __uint_as_float(u << 16); }
; __device__ __forceinline__ float bfhi(unsigned u) { return __uint_as_float(u & 0xFFFF0000u); }
; __device__ __forceinline__ float tanhf_(float x) { return 1.f - 2.f * rcpf_(1.f + __expf(2.f * x)); }
; __device__ __forceinline__ void phase_rwprep(const PP& p, int l) {
;     ...
;         const f32x4 c0 = (f32x4){bflo(cu.x), bfhi(cu.x), bflo(cu.y), bfhi(cu.y)}, c1 = (f32x4){bflo(cu.z), bfhi(cu.z), bflo(cu.w), bfhi(cu.w)};
;         const f32x4 a0 = (f32x4){bflo(pv.x), bfhi(pv.x), bflo(pv.y), bfhi(pv.y)}, a1 = (f32x4){bflo(pv.z), bfhi(pv.z), bflo(pv.w), bfhi(pv.w)};
;         const f32x4 n0 = (f32x4){bflo(nx.x), bfhi(nx.x), bflo(nx.y), bfhi(nx.y)}, n1 = (f32x4){bflo(nx.z), bfhi(nx.z), bflo(nx.w), bfhi(nx.w)};
;         f32x4 v0 = c0 + ((a0 + n0) * 0.5f - c0) * m0, v1 = c1 + ((a1 + n1) * 0.5f - c1) * m1;
;         if (col0 >= 768 && col0 < 832) {
; #pragma unroll
;             for (int i = 0; i < 4; ++i) { v0[i] = tanhf_(v0[i]); v1[i] = tanhf_(v1[i]); }
;         }
;         u32x4 o; o.x = pk2(v0[0], v0[1]); o.y = pk2(v0[2], v0[3]); o.z = pk2(v1[0], v1[1]); o.w = pk2(v1[2], v1[3]);
;         *(u32x4*)(RWP + (size_t)row * RWP_LD + col0) = o;
;     }
.Lrwp_noth_A:
	s_or_b64 exec, exec, s[24:25]
	v_cvt_pk_bf16_f32 v11, v2, v3
	v_mov_b64_e32 v[2:3], s[10:11]
	s_movk_i32 s6, 0x700
	v_mad_i64_i32 v[2:3], s[6:7], v1, s6, v[2:3]
	v_ashrrev_i32_e32 v19, 31, v18
	v_cvt_pk_bf16_f32 v8, v8, v9
	v_cvt_pk_bf16_f32 v9, v4, v5
	v_cvt_pk_bf16_f32 v10, v6, v7
	v_lshl_add_u64 v[2:3], v[18:19], 1, v[2:3]
	global_store_dwordx4 v[2:3], v[8:11], off
	s_mov_b64 exec, s[28:29]
	s_cbranch_execz .Lrwp_skipB2
	v_lshlrev_b32_e32 v72, 16, v44
	v_and_b32_e32 v73, 0xffff0000, v44
	v_lshlrev_b32_e32 v44, 16, v45
	v_and_b32_e32 v45, 0xffff0000, v45
	v_lshlrev_b32_e32 v74, 16, v46
	v_and_b32_e32 v75, 0xffff0000, v46
	v_lshlrev_b32_e32 v76, 16, v47
	v_and_b32_e32 v77, 0xffff0000, v47
	v_lshlrev_b32_e32 v46, 16, v52
	v_and_b32_e32 v47, 0xffff0000, v52
	v_lshlrev_b32_e32 v52, 16, v53
	v_and_b32_e32 v53, 0xffff0000, v53
	v_lshlrev_b32_e32 v78, 16, v54
	v_and_b32_e32 v79, 0xffff0000, v54
	v_lshlrev_b32_e32 v54, 16, v55
	v_and_b32_e32 v55, 0xffff0000, v55
	v_lshlrev_b32_e32 v80, 16, v48
	v_and_b32_e32 v81, 0xffff0000, v48
	v_lshlrev_b32_e32 v48, 16, v49
	v_and_b32_e32 v49, 0xffff0000, v49
	v_lshlrev_b32_e32 v82, 16, v50
	v_and_b32_e32 v83, 0xffff0000, v50
	v_lshlrev_b32_e32 v50, 16, v51
	v_and_b32_e32 v51, 0xffff0000, v51
	v_and_b32_e32 v57, -8, v62
	v_pk_add_f32 v[48:49], v[52:53], v[48:49]
	v_pk_add_f32 v[46:47], v[46:47], v[80:81]
	v_xor_b32_e32 v53, 0x80000000, v73
	v_xor_b32_e32 v52, 0x80000000, v72
	v_xor_b32_e32 v63, 0x80000000, v45
	v_xor_b32_e32 v62, 0x80000000, v44
	v_pk_add_f32 v[50:51], v[54:55], v[50:51]
	v_pk_add_f32 v[54:55], v[78:79], v[82:83]
	v_xor_b32_e32 v79, 0x80000000, v75
	v_xor_b32_e32 v78, 0x80000000, v74
	v_xor_b32_e32 v81, 0x80000000, v77
	v_xor_b32_e32 v80, 0x80000000, v76
	v_pk_fma_f32 v[52:53], v[46:47], 0.5, v[52:53] op_sel_hi:[1,0,1]
	v_pk_fma_f32 v[46:47], v[48:49], 0.5, v[62:63] op_sel_hi:[1,0,1]
	v_pk_fma_f32 v[48:49], v[54:55], 0.5, v[78:79] op_sel_hi:[1,0,1]
	v_pk_fma_f32 v[54:55], v[50:51], 0.5, v[80:81] op_sel_hi:[1,0,1]
	s_movk_i32 s6, 0x60
	v_cmp_eq_u32_e32 vcc, s6, v57
	v_pk_fma_f32 v[46:47], v[66:67], v[46:47], v[44:45]
	v_pk_fma_f32 v[50:51], v[64:65], v[52:53], v[72:73]
	v_pk_fma_f32 v[44:45], v[70:71], v[54:55], v[76:77]
	v_pk_fma_f32 v[48:49], v[68:69], v[48:49], v[74:75]
	s_and_saveexec_b64 s[24:25], vcc
	s_cbranch_execz .Lrwp_noth_B
	v_add_f32_e32 v44, v44, v44
	v_add_f32_e32 v47, v47, v47
	v_mul_f32_e32 v44, 0x3fb8aa3b, v44
	v_mul_f32_e32 v47, 0x3fb8aa3b, v47
	v_exp_f32_e32 v44, v44
	v_exp_f32_e32 v47, v47
	v_add_f32_e32 v48, v48, v48
	v_add_f32_e32 v51, v51, v51
	v_add_f32_e32 v49, v49, v49
	v_mul_f32_e32 v48, 0x3fb8aa3b, v48
	v_mul_f32_e32 v51, 0x3fb8aa3b, v51
	v_mul_f32_e32 v49, 0x3fb8aa3b, v49
	v_exp_f32_e32 v48, v48
	v_exp_f32_e32 v51, v51
	v_exp_f32_e32 v49, v49
	v_add_f32_e32 v53, 1.0, v44
	v_add_f32_e32 v44, 1.0, v47
	v_add_f32_e32 v50, v50, v50
	v_add_f32_e32 v46, v46, v46
	v_rcp_f32_e64 v47, -v44
	v_add_f32_e32 v44, v45, v45
	v_mul_f32_e32 v50, 0x3fb8aa3b, v50
	v_mul_f32_e32 v46, 0x3fb8aa3b, v46
	v_mul_f32_e32 v44, 0x3fb8aa3b, v44
	v_exp_f32_e32 v50, v50
	v_add_f32_e32 v52, 1.0, v48
	v_add_f32_e32 v48, 1.0, v51
	v_exp_f32_e32 v46, v46
	v_add_f32_e32 v51, 1.0, v49
	v_exp_f32_e32 v49, v44
	v_add_f32_e32 v50, 1.0, v50
	v_add_f32_e32 v46, 1.0, v46
	v_rcp_f32_e64 v45, -v48
	v_add_f32_e32 v48, 1.0, v49
	v_rcp_f32_e64 v46, -v46
	v_rcp_f32_e64 v44, -v50
	v_rcp_f32_e64 v49, -v48
	v_rcp_f32_e64 v48, -v53
	v_rcp_f32_e64 v53, -v51
	v_rcp_f32_e64 v52, -v52
	v_pk_fma_f32 v[46:47], v[46:47], 2.0, 1.0 op_sel_hi:[1,0,0]
	v_pk_fma_f32 v[50:51], v[44:45], 2.0, 1.0 op_sel_hi:[1,0,0]
	v_pk_fma_f32 v[44:45], v[48:49], 2.0, 1.0 op_sel_hi:[1,0,0]
	v_pk_fma_f32 v[48:49], v[52:53], 2.0, 1.0 op_sel_hi:[1,0,0]
.Lrwp_noth_B:
	s_or_b64 exec, exec, s[24:25]
	v_cvt_pk_bf16_f32 v53, v44, v45
	v_mov_b64_e32 v[44:45], s[10:11]
	s_movk_i32 s6, 0x700
	v_mad_i64_i32 v[44:45], s[6:7], v43, s6, v[44:45]
	v_ashrrev_i32_e32 v61, 31, v60
	v_cvt_pk_bf16_f32 v50, v50, v51
	v_cvt_pk_bf16_f32 v51, v46, v47
	v_cvt_pk_bf16_f32 v52, v48, v49
	v_lshl_add_u64 v[44:45], v[60:61], 1, v[44:45]
	global_store_dwordx4 v[44:45], v[50:53], off
.Lrwp_skipB2:
	s_mov_b64 exec, s[36:37]
	v_lshl_add_u32 v14, s98, 1, v14
	v_lshl_add_u32 v16, s98, 4, v16
	v_cmp_lt_i32_e32 vcc, s99, v14
	s_or_b64 s[22:23], vcc, s[22:23]
	s_andn2_b64 exec, exec, s[22:23]
	s_cbranch_execnz .LBB0_386
